# experiment: nt on the weight (B operand) LDS-DMA loads of the two N=11264 GEMM K-loops
# baseline (speedup 1.0000x reference)
.LBB0_150:
	ds_read_b128 v[130:133], v220
	ds_read_b128 v[134:137], v220 offset:1024
	ds_read_b128 v[138:141], v220 offset:2048
	ds_read_b128 v[142:145], v220 offset:3072
	ds_read_b128 v[164:167], v221
	ds_read_b128 v[168:171], v221 offset:1024
	ds_read_b128 v[172:175], v221 offset:2048
	ds_read_b128 v[176:179], v221 offset:3072
	s_add_u32 s28, s6, 0xfff80080
	s_addc_u32 s29, s7, -1
	s_cmp_eq_u32 s35, 28
	s_cselect_b32 s31, s1, s29
	s_cselect_b32 s30, s5, s28
	s_cselect_b32 s29, s21, s34
	s_cselect_b32 s28, s23, s33
	v_lshl_add_u64 v[212:213], s[6:7], 0, v[156:157]
	s_add_i32 m0, s40, 0xc000
	ds_read_b128 v[180:183], v222
	ds_read_b128 v[184:187], v222 offset:1024
	ds_read_b128 v[188:191], v222 offset:2048
	ds_read_b128 v[192:195], v222 offset:3072
	ds_read_b128 v[196:199], v222 offset:4096
	ds_read_b128 v[200:203], v222 offset:5120
	ds_read_b128 v[204:207], v222 offset:6144
	ds_read_b128 v[208:211], v222 offset:7168
	global_load_lds_dwordx4 v[212:213], off
	v_lshl_add_u64 v[212:213], s[6:7], 0, v[158:159]
	s_add_i32 m0, s40, 0xe000
	s_nop 0
	global_load_lds_dwordx4 v[212:213], off
	s_waitcnt vmcnt(8)
	s_waitcnt lgkmcnt(0)
	s_barrier
	s_setprio 1
	s_waitcnt lgkmcnt(0)
	v_mfma_f32_16x16x32_bf16 v[126:129], v[130:133], v[180:183], v[126:129]
	v_mfma_f32_16x16x32_bf16 v[122:125], v[138:141], v[180:183], v[122:125]
	v_mfma_f32_16x16x32_bf16 v[110:113], v[130:133], v[188:191], v[110:113]
	v_mfma_f32_16x16x32_bf16 v[106:109], v[138:141], v[188:191], v[106:109]
	v_mfma_f32_16x16x32_bf16 v[94:97], v[130:133], v[196:199], v[94:97]
	v_mfma_f32_16x16x32_bf16 v[90:93], v[138:141], v[196:199], v[90:93]
	v_mfma_f32_16x16x32_bf16 v[78:81], v[130:133], v[204:207], v[78:81]
	v_mfma_f32_16x16x32_bf16 v[74:77], v[138:141], v[204:207], v[74:77]
	v_mfma_f32_16x16x32_bf16 v[126:129], v[134:137], v[184:187], v[126:129]
	v_mfma_f32_16x16x32_bf16 v[122:125], v[142:145], v[184:187], v[122:125]
	v_mfma_f32_16x16x32_bf16 v[110:113], v[134:137], v[192:195], v[110:113]
	v_mfma_f32_16x16x32_bf16 v[106:109], v[142:145], v[192:195], v[106:109]
	v_mfma_f32_16x16x32_bf16 v[94:97], v[134:137], v[200:203], v[94:97]
	v_mfma_f32_16x16x32_bf16 v[90:93], v[142:145], v[200:203], v[90:93]
	v_mfma_f32_16x16x32_bf16 v[78:81], v[134:137], v[208:211], v[78:81]
	v_mfma_f32_16x16x32_bf16 v[74:77], v[142:145], v[208:211], v[74:77]
	s_setprio 0
	s_setprio 1
	v_mfma_f32_16x16x32_bf16 v[118:121], v[164:167], v[180:183], v[118:121]
	v_mfma_f32_16x16x32_bf16 v[114:117], v[172:175], v[180:183], v[114:117]
	v_mfma_f32_16x16x32_bf16 v[102:105], v[164:167], v[188:191], v[102:105]
	v_mfma_f32_16x16x32_bf16 v[98:101], v[172:175], v[188:191], v[98:101]
	v_mfma_f32_16x16x32_bf16 v[86:89], v[164:167], v[196:199], v[86:89]
	v_mfma_f32_16x16x32_bf16 v[82:85], v[172:175], v[196:199], v[82:85]
	v_mfma_f32_16x16x32_bf16 v[70:73], v[164:167], v[204:207], v[70:73]
	v_mfma_f32_16x16x32_bf16 v[66:69], v[172:175], v[204:207], v[66:69]
	v_mfma_f32_16x16x32_bf16 v[118:121], v[168:171], v[184:187], v[118:121]
	v_mfma_f32_16x16x32_bf16 v[114:117], v[176:179], v[184:187], v[114:117]
	v_mfma_f32_16x16x32_bf16 v[102:105], v[168:171], v[192:195], v[102:105]
	v_mfma_f32_16x16x32_bf16 v[98:101], v[176:179], v[192:195], v[98:101]
	v_mfma_f32_16x16x32_bf16 v[86:89], v[168:171], v[200:203], v[86:89]
	v_mfma_f32_16x16x32_bf16 v[82:85], v[176:179], v[200:203], v[82:85]
	v_mfma_f32_16x16x32_bf16 v[70:73], v[168:171], v[208:211], v[70:73]
	v_mfma_f32_16x16x32_bf16 v[66:69], v[176:179], v[208:211], v[66:69]
	s_setprio 0
	s_barrier
	s_add_i32 s68, s94, s39
	v_lshl_add_u64 v[212:213], s[28:29], 0, v[148:149]
	s_mov_b32 m0, s68
	ds_read_b128 v[180:183], v222 offset:16384
	ds_read_b128 v[184:187], v222 offset:17408
	ds_read_b128 v[188:191], v222 offset:18432
	ds_read_b128 v[192:195], v222 offset:19456
	ds_read_b128 v[196:199], v222 offset:20480
	ds_read_b128 v[200:203], v222 offset:21504
	ds_read_b128 v[204:207], v222 offset:22528
	ds_read_b128 v[208:211], v222 offset:23552
	global_load_lds_dwordx4 v[212:213], off nt
	s_add_i32 m0, s68, 0x2000
	s_add_u32 s68, s28, 0x80000
	v_lshl_add_u64 v[214:215], s[28:29], 0, v[152:153]
	s_addc_u32 s69, s29, 0
	s_add_i32 s70, s96, s39
	global_load_lds_dwordx4 v[214:215], off nt
	v_lshl_add_u64 v[226:227], s[68:69], 0, v[148:149]
	s_mov_b32 m0, s70
	v_lshl_add_u64 v[228:229], s[30:31], 0, v[150:151]
	global_load_lds_dwordx4 v[226:227], off nt
	v_lshl_add_u64 v[226:227], s[68:69], 0, v[152:153]
	s_add_i32 m0, s70, 0x2000
	s_nop 0
	global_load_lds_dwordx4 v[226:227], off nt
	v_lshl_add_u64 v[226:227], s[30:31], 0, v[146:147]
	s_mov_b32 m0, s40
	s_nop 0
	global_load_lds_dwordx4 v[226:227], off
	s_mov_b32 m0, s41
	s_nop 0
	global_load_lds_dwordx4 v[228:229], off
	s_waitcnt vmcnt(8)
	s_waitcnt lgkmcnt(0)
	s_barrier
	s_setprio 1
	s_waitcnt lgkmcnt(0)
	v_mfma_f32_16x16x32_bf16 v[62:65], v[130:133], v[180:183], v[62:65]
	v_mfma_f32_16x16x32_bf16 v[58:61], v[138:141], v[180:183], v[58:61]
	v_mfma_f32_16x16x32_bf16 v[46:49], v[130:133], v[188:191], v[46:49]
	v_mfma_f32_16x16x32_bf16 v[42:45], v[138:141], v[188:191], v[42:45]
	v_mfma_f32_16x16x32_bf16 v[30:33], v[130:133], v[196:199], v[30:33]
	v_mfma_f32_16x16x32_bf16 v[26:29], v[138:141], v[196:199], v[26:29]
	v_mfma_f32_16x16x32_bf16 v[14:17], v[130:133], v[204:207], v[14:17]
	v_mfma_f32_16x16x32_bf16 v[10:13], v[138:141], v[204:207], v[10:13]
	v_mfma_f32_16x16x32_bf16 v[62:65], v[134:137], v[184:187], v[62:65]
	v_mfma_f32_16x16x32_bf16 v[58:61], v[142:145], v[184:187], v[58:61]
	v_mfma_f32_16x16x32_bf16 v[46:49], v[134:137], v[192:195], v[46:49]
	v_mfma_f32_16x16x32_bf16 v[42:45], v[142:145], v[192:195], v[42:45]
	v_mfma_f32_16x16x32_bf16 v[30:33], v[134:137], v[200:203], v[30:33]
	v_mfma_f32_16x16x32_bf16 v[26:29], v[142:145], v[200:203], v[26:29]
	v_mfma_f32_16x16x32_bf16 v[14:17], v[134:137], v[208:211], v[14:17]
	v_mfma_f32_16x16x32_bf16 v[10:13], v[142:145], v[208:211], v[10:13]
	s_setprio 0
	s_setprio 1
	v_mfma_f32_16x16x32_bf16 v[54:57], v[164:167], v[180:183], v[54:57]
	v_mfma_f32_16x16x32_bf16 v[50:53], v[172:175], v[180:183], v[50:53]
	v_mfma_f32_16x16x32_bf16 v[38:41], v[164:167], v[188:191], v[38:41]
	v_mfma_f32_16x16x32_bf16 v[34:37], v[172:175], v[188:191], v[34:37]
	v_mfma_f32_16x16x32_bf16 v[22:25], v[164:167], v[196:199], v[22:25]
	v_mfma_f32_16x16x32_bf16 v[18:21], v[172:175], v[196:199], v[18:21]
	v_mfma_f32_16x16x32_bf16 v[6:9], v[164:167], v[204:207], v[6:9]
	v_mfma_f32_16x16x32_bf16 v[2:5], v[172:175], v[204:207], v[2:5]
	v_mfma_f32_16x16x32_bf16 v[54:57], v[168:171], v[184:187], v[54:57]
	v_mfma_f32_16x16x32_bf16 v[50:53], v[176:179], v[184:187], v[50:53]
	v_mfma_f32_16x16x32_bf16 v[38:41], v[168:171], v[192:195], v[38:41]
	v_mfma_f32_16x16x32_bf16 v[34:37], v[176:179], v[192:195], v[34:37]
	v_mfma_f32_16x16x32_bf16 v[22:25], v[168:171], v[200:203], v[22:25]
	v_mfma_f32_16x16x32_bf16 v[18:21], v[176:179], v[200:203], v[18:21]
	v_mfma_f32_16x16x32_bf16 v[6:9], v[168:171], v[208:211], v[6:9]
	v_mfma_f32_16x16x32_bf16 v[2:5], v[176:179], v[208:211], v[2:5]
	s_setprio 0
	s_barrier
	s_add_i32 s68, 0, 0x18000
	s_add_i32 s69, 0, 0x1c000
	v_add_u32_e32 v142, s68, v218
	v_add_u32_e32 v154, s69, v218
	ds_read_b128 v[130:133], v142
	ds_read_b128 v[134:137], v142 offset:1024
	ds_read_b128 v[138:141], v142 offset:2048
	ds_read_b128 v[142:145], v142 offset:3072
	ds_read_b128 v[164:167], v154
	ds_read_b128 v[168:171], v154 offset:1024
	ds_read_b128 v[172:175], v154 offset:2048
	ds_read_b128 v[176:179], v154 offset:3072
	s_add_u32 s30, s30, 0x80000
	s_addc_u32 s31, s31, 0
	s_mov_b32 m0, s42
	v_lshl_add_u64 v[230:231], s[30:31], 0, v[146:147]
	ds_read_b128 v[180:183], v222 offset:32768
	ds_read_b128 v[184:187], v222 offset:33792
	ds_read_b128 v[188:191], v222 offset:34816
	ds_read_b128 v[192:195], v222 offset:35840
	ds_read_b128 v[196:199], v222 offset:36864
	ds_read_b128 v[200:203], v222 offset:37888
	ds_read_b128 v[204:207], v222 offset:38912
	ds_read_b128 v[208:211], v222 offset:39936
	global_load_lds_dwordx4 v[230:231], off
	v_lshl_add_u64 v[230:231], s[30:31], 0, v[150:151]
	s_mov_b32 m0, s43
	s_nop 0
	global_load_lds_dwordx4 v[230:231], off
	s_waitcnt vmcnt(8)
	s_waitcnt lgkmcnt(0)
	s_barrier
	s_setprio 1
	s_waitcnt lgkmcnt(0)
	v_mfma_f32_16x16x32_bf16 v[126:129], v[130:133], v[180:183], v[126:129]
	v_mfma_f32_16x16x32_bf16 v[122:125], v[138:141], v[180:183], v[122:125]
	v_mfma_f32_16x16x32_bf16 v[110:113], v[130:133], v[188:191], v[110:113]
	v_mfma_f32_16x16x32_bf16 v[106:109], v[138:141], v[188:191], v[106:109]
	v_mfma_f32_16x16x32_bf16 v[94:97], v[130:133], v[196:199], v[94:97]
	v_mfma_f32_16x16x32_bf16 v[90:93], v[138:141], v[196:199], v[90:93]
	v_mfma_f32_16x16x32_bf16 v[78:81], v[130:133], v[204:207], v[78:81]
	v_mfma_f32_16x16x32_bf16 v[74:77], v[138:141], v[204:207], v[74:77]
	v_mfma_f32_16x16x32_bf16 v[126:129], v[134:137], v[184:187], v[126:129]
	v_mfma_f32_16x16x32_bf16 v[122:125], v[142:145], v[184:187], v[122:125]
	v_mfma_f32_16x16x32_bf16 v[110:113], v[134:137], v[192:195], v[110:113]
	v_mfma_f32_16x16x32_bf16 v[106:109], v[142:145], v[192:195], v[106:109]
	v_mfma_f32_16x16x32_bf16 v[94:97], v[134:137], v[200:203], v[94:97]
	v_mfma_f32_16x16x32_bf16 v[90:93], v[142:145], v[200:203], v[90:93]
	v_mfma_f32_16x16x32_bf16 v[78:81], v[134:137], v[208:211], v[78:81]
	v_mfma_f32_16x16x32_bf16 v[74:77], v[142:145], v[208:211], v[74:77]
	s_setprio 0
	s_setprio 1
	v_mfma_f32_16x16x32_bf16 v[118:121], v[164:167], v[180:183], v[118:121]
	v_mfma_f32_16x16x32_bf16 v[114:117], v[172:175], v[180:183], v[114:117]
	v_mfma_f32_16x16x32_bf16 v[102:105], v[164:167], v[188:191], v[102:105]
	v_mfma_f32_16x16x32_bf16 v[98:101], v[172:175], v[188:191], v[98:101]
	v_mfma_f32_16x16x32_bf16 v[86:89], v[164:167], v[196:199], v[86:89]
	v_mfma_f32_16x16x32_bf16 v[82:85], v[172:175], v[196:199], v[82:85]
	v_mfma_f32_16x16x32_bf16 v[70:73], v[164:167], v[204:207], v[70:73]
	v_mfma_f32_16x16x32_bf16 v[66:69], v[172:175], v[204:207], v[66:69]
	v_mfma_f32_16x16x32_bf16 v[118:121], v[168:171], v[184:187], v[118:121]
	v_mfma_f32_16x16x32_bf16 v[114:117], v[176:179], v[184:187], v[114:117]
	v_mfma_f32_16x16x32_bf16 v[102:105], v[168:171], v[192:195], v[102:105]
	v_mfma_f32_16x16x32_bf16 v[98:101], v[176:179], v[192:195], v[98:101]
	v_mfma_f32_16x16x32_bf16 v[86:89], v[168:171], v[200:203], v[86:89]
	v_mfma_f32_16x16x32_bf16 v[82:85], v[176:179], v[200:203], v[82:85]
	v_mfma_f32_16x16x32_bf16 v[70:73], v[168:171], v[208:211], v[70:73]
	v_mfma_f32_16x16x32_bf16 v[66:69], v[176:179], v[208:211], v[66:69]
	s_setprio 0
	s_barrier
	s_add_i32 s30, s68, s39
	v_lshl_add_u64 v[212:213], v[212:213], 0, s[14:15]
	s_mov_b32 m0, s30
	ds_read_b128 v[180:183], v222 offset:49152
	ds_read_b128 v[184:187], v222 offset:50176
	ds_read_b128 v[188:191], v222 offset:51200
	ds_read_b128 v[192:195], v222 offset:52224
	ds_read_b128 v[196:199], v222 offset:53248
	ds_read_b128 v[200:203], v222 offset:54272
	ds_read_b128 v[204:207], v222 offset:55296
	ds_read_b128 v[208:211], v222 offset:56320
	global_load_lds_dwordx4 v[212:213], off nt
	s_add_i32 m0, s30, 0x2000
	s_add_u32 s28, s28, 0x80080
	v_lshl_add_u64 v[212:213], v[214:215], 0, s[14:15]
	s_addc_u32 s29, s29, 0
	s_add_i32 s30, s69, s39
	global_load_lds_dwordx4 v[212:213], off nt
	v_lshl_add_u64 v[212:213], s[28:29], 0, v[148:149]
	s_mov_b32 m0, s30
	s_nop 0
	global_load_lds_dwordx4 v[212:213], off nt
	v_lshl_add_u64 v[212:213], s[28:29], 0, v[152:153]
	s_add_i32 m0, s30, 0x2000
	s_nop 0
	global_load_lds_dwordx4 v[212:213], off nt
	v_lshl_add_u64 v[212:213], v[226:227], 0, s[14:15]
	s_mov_b32 m0, s87
	s_nop 0
	global_load_lds_dwordx4 v[212:213], off
	v_lshl_add_u64 v[212:213], v[228:229], 0, s[14:15]
	s_mov_b32 m0, s92
	s_nop 0
	global_load_lds_dwordx4 v[212:213], off
	s_waitcnt vmcnt(8)
	s_waitcnt lgkmcnt(0)
	s_barrier
	s_setprio 1
	s_waitcnt lgkmcnt(0)
	v_mfma_f32_16x16x32_bf16 v[62:65], v[130:133], v[180:183], v[62:65]
	v_mfma_f32_16x16x32_bf16 v[58:61], v[138:141], v[180:183], v[58:61]
	v_mfma_f32_16x16x32_bf16 v[46:49], v[130:133], v[188:191], v[46:49]
	v_mfma_f32_16x16x32_bf16 v[42:45], v[138:141], v[188:191], v[42:45]
	v_mfma_f32_16x16x32_bf16 v[30:33], v[130:133], v[196:199], v[30:33]
	v_mfma_f32_16x16x32_bf16 v[26:29], v[138:141], v[196:199], v[26:29]
	v_mfma_f32_16x16x32_bf16 v[14:17], v[130:133], v[204:207], v[14:17]
	v_mfma_f32_16x16x32_bf16 v[10:13], v[138:141], v[204:207], v[10:13]
	v_mfma_f32_16x16x32_bf16 v[62:65], v[134:137], v[184:187], v[62:65]
	v_mfma_f32_16x16x32_bf16 v[58:61], v[142:145], v[184:187], v[58:61]
	v_mfma_f32_16x16x32_bf16 v[46:49], v[134:137], v[192:195], v[46:49]
	v_mfma_f32_16x16x32_bf16 v[42:45], v[142:145], v[192:195], v[42:45]
	v_mfma_f32_16x16x32_bf16 v[30:33], v[134:137], v[200:203], v[30:33]
	v_mfma_f32_16x16x32_bf16 v[26:29], v[142:145], v[200:203], v[26:29]
	v_mfma_f32_16x16x32_bf16 v[14:17], v[134:137], v[208:211], v[14:17]
	v_mfma_f32_16x16x32_bf16 v[10:13], v[142:145], v[208:211], v[10:13]
	s_setprio 0
	s_setprio 1
	v_mfma_f32_16x16x32_bf16 v[54:57], v[164:167], v[180:183], v[54:57]
	v_mfma_f32_16x16x32_bf16 v[50:53], v[172:175], v[180:183], v[50:53]
	v_mfma_f32_16x16x32_bf16 v[38:41], v[164:167], v[188:191], v[38:41]
	v_mfma_f32_16x16x32_bf16 v[34:37], v[172:175], v[188:191], v[34:37]
	v_mfma_f32_16x16x32_bf16 v[22:25], v[164:167], v[196:199], v[22:25]
	v_mfma_f32_16x16x32_bf16 v[18:21], v[172:175], v[196:199], v[18:21]
	v_mfma_f32_16x16x32_bf16 v[6:9], v[164:167], v[204:207], v[6:9]
	v_mfma_f32_16x16x32_bf16 v[2:5], v[172:175], v[204:207], v[2:5]
	v_mfma_f32_16x16x32_bf16 v[54:57], v[168:171], v[184:187], v[54:57]
	v_mfma_f32_16x16x32_bf16 v[50:53], v[176:179], v[184:187], v[50:53]
	v_mfma_f32_16x16x32_bf16 v[38:41], v[168:171], v[192:195], v[38:41]
	v_mfma_f32_16x16x32_bf16 v[34:37], v[176:179], v[192:195], v[34:37]
	v_mfma_f32_16x16x32_bf16 v[22:25], v[168:171], v[200:203], v[22:25]
	v_mfma_f32_16x16x32_bf16 v[18:21], v[176:179], v[200:203], v[18:21]
	v_mfma_f32_16x16x32_bf16 v[6:9], v[168:171], v[208:211], v[6:9]
	v_mfma_f32_16x16x32_bf16 v[2:5], v[176:179], v[208:211], v[2:5]
	s_setprio 0
	s_barrier
	s_add_i32 s35, s35, 2
	s_add_u32 s6, s6, 0x100
	s_addc_u32 s7, s7, 0
	s_add_u32 s33, s33, 0x100
	s_addc_u32 s34, s34, 0
	s_cmp_gt_u32 s35, 29
	s_cbranch_scc0 .LBB0_150
	s_and_b64 vcc, exec, s[88:89]
	s_cbranch_vccz .LBB0_153
	s_barrier

.LBB0_1135:
	ds_read_b128 v[152:155], v149
	ds_read_b128 v[156:159], v149 offset:1024
	ds_read_b128 v[160:163], v149 offset:2048
	ds_read_b128 v[164:167], v149 offset:3072
	ds_read_b128 v[168:171], v150
	ds_read_b128 v[172:175], v150 offset:1024
	ds_read_b128 v[176:179], v150 offset:2048
	ds_read_b128 v[180:183], v150 offset:3072
	s_add_u32 s22, s20, 0xfff80080
	s_addc_u32 s23, s21, -1
	s_cmp_eq_u32 s48, 28
	s_cselect_b32 s25, s13, s23
	s_cselect_b32 s24, s44, s22
	s_cselect_b32 s23, s11, s47
	s_cselect_b32 s22, s45, s46
	v_lshl_add_u64 v[216:217], s[20:21], 0, v[138:139]
	s_add_i32 m0, s19, 0xc000
	ds_read_b128 v[184:187], v151
	ds_read_b128 v[188:191], v151 offset:1024
	ds_read_b128 v[192:195], v151 offset:2048
	ds_read_b128 v[196:199], v151 offset:3072
	ds_read_b128 v[200:203], v151 offset:4096
	ds_read_b128 v[204:207], v151 offset:5120
	ds_read_b128 v[208:211], v151 offset:6144
	ds_read_b128 v[212:215], v151 offset:7168
	global_load_lds_dwordx4 v[216:217], off
	v_lshl_add_u64 v[216:217], s[20:21], 0, v[140:141]
	s_add_i32 m0, s19, 0xe000
	s_nop 0
	global_load_lds_dwordx4 v[216:217], off
	s_waitcnt vmcnt(8)
	s_waitcnt lgkmcnt(0)
	s_barrier
	s_setprio 1
	s_waitcnt lgkmcnt(0)
	v_mfma_f32_16x16x32_bf16 v[126:129], v[152:155], v[184:187], v[126:129]
	v_mfma_f32_16x16x32_bf16 v[122:125], v[160:163], v[184:187], v[122:125]
	v_mfma_f32_16x16x32_bf16 v[110:113], v[152:155], v[192:195], v[110:113]
	v_mfma_f32_16x16x32_bf16 v[106:109], v[160:163], v[192:195], v[106:109]
	v_mfma_f32_16x16x32_bf16 v[94:97], v[152:155], v[200:203], v[94:97]
	v_mfma_f32_16x16x32_bf16 v[90:93], v[160:163], v[200:203], v[90:93]
	v_mfma_f32_16x16x32_bf16 v[78:81], v[152:155], v[208:211], v[78:81]
	v_mfma_f32_16x16x32_bf16 v[74:77], v[160:163], v[208:211], v[74:77]
	v_mfma_f32_16x16x32_bf16 v[126:129], v[156:159], v[188:191], v[126:129]
	v_mfma_f32_16x16x32_bf16 v[122:125], v[164:167], v[188:191], v[122:125]
	v_mfma_f32_16x16x32_bf16 v[110:113], v[156:159], v[196:199], v[110:113]
	v_mfma_f32_16x16x32_bf16 v[106:109], v[164:167], v[196:199], v[106:109]
	v_mfma_f32_16x16x32_bf16 v[94:97], v[156:159], v[204:207], v[94:97]
	v_mfma_f32_16x16x32_bf16 v[90:93], v[164:167], v[204:207], v[90:93]
	v_mfma_f32_16x16x32_bf16 v[78:81], v[156:159], v[212:215], v[78:81]
	v_mfma_f32_16x16x32_bf16 v[74:77], v[164:167], v[212:215], v[74:77]
	s_setprio 0
	s_setprio 1
	v_mfma_f32_16x16x32_bf16 v[118:121], v[168:171], v[184:187], v[118:121]
	v_mfma_f32_16x16x32_bf16 v[114:117], v[176:179], v[184:187], v[114:117]
	v_mfma_f32_16x16x32_bf16 v[102:105], v[168:171], v[192:195], v[102:105]
	v_mfma_f32_16x16x32_bf16 v[98:101], v[176:179], v[192:195], v[98:101]
	v_mfma_f32_16x16x32_bf16 v[86:89], v[168:171], v[200:203], v[86:89]
	v_mfma_f32_16x16x32_bf16 v[82:85], v[176:179], v[200:203], v[82:85]
	v_mfma_f32_16x16x32_bf16 v[70:73], v[168:171], v[208:211], v[70:73]
	v_mfma_f32_16x16x32_bf16 v[66:69], v[176:179], v[208:211], v[66:69]
	v_mfma_f32_16x16x32_bf16 v[118:121], v[172:175], v[188:191], v[118:121]
	v_mfma_f32_16x16x32_bf16 v[114:117], v[180:183], v[188:191], v[114:117]
	v_mfma_f32_16x16x32_bf16 v[102:105], v[172:175], v[196:199], v[102:105]
	v_mfma_f32_16x16x32_bf16 v[98:101], v[180:183], v[196:199], v[98:101]
	v_mfma_f32_16x16x32_bf16 v[86:89], v[172:175], v[204:207], v[86:89]
	v_mfma_f32_16x16x32_bf16 v[82:85], v[180:183], v[204:207], v[82:85]
	v_mfma_f32_16x16x32_bf16 v[70:73], v[172:175], v[212:215], v[70:73]
	v_mfma_f32_16x16x32_bf16 v[66:69], v[180:183], v[212:215], v[66:69]
	s_setprio 0
	s_barrier
	s_add_i32 s49, s40, s30
	v_lshl_add_u64 v[216:217], s[22:23], 0, v[132:133]
	s_mov_b32 m0, s49
	ds_read_b128 v[184:187], v151 offset:16384
	ds_read_b128 v[188:191], v151 offset:17408
	ds_read_b128 v[192:195], v151 offset:18432
	ds_read_b128 v[196:199], v151 offset:19456
	ds_read_b128 v[200:203], v151 offset:20480
	ds_read_b128 v[204:207], v151 offset:21504
	ds_read_b128 v[208:211], v151 offset:22528
	ds_read_b128 v[212:215], v151 offset:23552
	global_load_lds_dwordx4 v[216:217], off nt
	s_add_i32 m0, s49, 0x2000
	s_add_u32 s50, s22, 0x80000
	v_lshl_add_u64 v[218:219], s[22:23], 0, v[136:137]
	s_addc_u32 s51, s23, 0
	s_add_i32 s49, s41, s30
	global_load_lds_dwordx4 v[218:219], off nt
	v_lshl_add_u64 v[220:221], s[50:51], 0, v[132:133]
	s_mov_b32 m0, s49
	v_lshl_add_u64 v[222:223], s[24:25], 0, v[134:135]
	global_load_lds_dwordx4 v[220:221], off nt
	v_lshl_add_u64 v[220:221], s[50:51], 0, v[136:137]
	s_add_i32 m0, s49, 0x2000
	s_nop 0
	global_load_lds_dwordx4 v[220:221], off nt
	v_lshl_add_u64 v[220:221], s[24:25], 0, v[130:131]
	s_mov_b32 m0, s19
	s_nop 0
	global_load_lds_dwordx4 v[220:221], off
	s_mov_b32 m0, s33
	s_nop 0
	global_load_lds_dwordx4 v[222:223], off
	s_waitcnt vmcnt(8)
	s_waitcnt lgkmcnt(0)
	s_barrier
	s_setprio 1
	s_waitcnt lgkmcnt(0)
	v_mfma_f32_16x16x32_bf16 v[62:65], v[152:155], v[184:187], v[62:65]
	v_mfma_f32_16x16x32_bf16 v[58:61], v[160:163], v[184:187], v[58:61]
	v_mfma_f32_16x16x32_bf16 v[46:49], v[152:155], v[192:195], v[46:49]
	v_mfma_f32_16x16x32_bf16 v[42:45], v[160:163], v[192:195], v[42:45]
	v_mfma_f32_16x16x32_bf16 v[30:33], v[152:155], v[200:203], v[30:33]
	v_mfma_f32_16x16x32_bf16 v[26:29], v[160:163], v[200:203], v[26:29]
	v_mfma_f32_16x16x32_bf16 v[14:17], v[152:155], v[208:211], v[14:17]
	v_mfma_f32_16x16x32_bf16 v[10:13], v[160:163], v[208:211], v[10:13]
	v_mfma_f32_16x16x32_bf16 v[62:65], v[156:159], v[188:191], v[62:65]
	v_mfma_f32_16x16x32_bf16 v[58:61], v[164:167], v[188:191], v[58:61]
	v_mfma_f32_16x16x32_bf16 v[46:49], v[156:159], v[196:199], v[46:49]
	v_mfma_f32_16x16x32_bf16 v[42:45], v[164:167], v[196:199], v[42:45]
	v_mfma_f32_16x16x32_bf16 v[30:33], v[156:159], v[204:207], v[30:33]
	v_mfma_f32_16x16x32_bf16 v[26:29], v[164:167], v[204:207], v[26:29]
	v_mfma_f32_16x16x32_bf16 v[14:17], v[156:159], v[212:215], v[14:17]
	v_mfma_f32_16x16x32_bf16 v[10:13], v[164:167], v[212:215], v[10:13]
	s_setprio 0
	s_setprio 1
	v_mfma_f32_16x16x32_bf16 v[54:57], v[168:171], v[184:187], v[54:57]
	v_mfma_f32_16x16x32_bf16 v[50:53], v[176:179], v[184:187], v[50:53]
	v_mfma_f32_16x16x32_bf16 v[38:41], v[168:171], v[192:195], v[38:41]
	v_mfma_f32_16x16x32_bf16 v[34:37], v[176:179], v[192:195], v[34:37]
	v_mfma_f32_16x16x32_bf16 v[22:25], v[168:171], v[200:203], v[22:25]
	v_mfma_f32_16x16x32_bf16 v[18:21], v[176:179], v[200:203], v[18:21]
	v_mfma_f32_16x16x32_bf16 v[6:9], v[168:171], v[208:211], v[6:9]
	v_mfma_f32_16x16x32_bf16 v[2:5], v[176:179], v[208:211], v[2:5]
	v_mfma_f32_16x16x32_bf16 v[54:57], v[172:175], v[188:191], v[54:57]
	v_mfma_f32_16x16x32_bf16 v[50:53], v[180:183], v[188:191], v[50:53]
	v_mfma_f32_16x16x32_bf16 v[38:41], v[172:175], v[196:199], v[38:41]
	v_mfma_f32_16x16x32_bf16 v[34:37], v[180:183], v[196:199], v[34:37]
	v_mfma_f32_16x16x32_bf16 v[22:25], v[172:175], v[204:207], v[22:25]
	v_mfma_f32_16x16x32_bf16 v[18:21], v[180:183], v[204:207], v[18:21]
	v_mfma_f32_16x16x32_bf16 v[6:9], v[172:175], v[212:215], v[6:9]
	v_mfma_f32_16x16x32_bf16 v[2:5], v[180:183], v[212:215], v[2:5]
	s_setprio 0
	s_barrier
	s_add_i32 s49, 0, 0x18000
	s_add_i32 s50, 0, 0x1c000
	v_add_u32_e32 v164, s49, v147
	v_add_u32_e32 v180, s50, v147
	ds_read_b128 v[152:155], v164
	ds_read_b128 v[156:159], v164 offset:1024
	ds_read_b128 v[160:163], v164 offset:2048
	ds_read_b128 v[164:167], v164 offset:3072
	ds_read_b128 v[168:171], v180
	ds_read_b128 v[172:175], v180 offset:1024
	ds_read_b128 v[176:179], v180 offset:2048
	ds_read_b128 v[180:183], v180 offset:3072
	s_add_u32 s24, s24, 0x80000
	s_addc_u32 s25, s25, 0
	s_mov_b32 m0, s34
	v_lshl_add_u64 v[224:225], s[24:25], 0, v[130:131]
	ds_read_b128 v[184:187], v151 offset:32768
	ds_read_b128 v[188:191], v151 offset:33792
	ds_read_b128 v[192:195], v151 offset:34816
	ds_read_b128 v[196:199], v151 offset:35840
	ds_read_b128 v[200:203], v151 offset:36864
	ds_read_b128 v[204:207], v151 offset:37888
	ds_read_b128 v[208:211], v151 offset:38912
	ds_read_b128 v[212:215], v151 offset:39936
	global_load_lds_dwordx4 v[224:225], off
	v_lshl_add_u64 v[224:225], s[24:25], 0, v[134:135]
	s_mov_b32 m0, s35
	s_nop 0
	global_load_lds_dwordx4 v[224:225], off
	s_waitcnt vmcnt(8)
	s_waitcnt lgkmcnt(0)
	s_barrier
	s_setprio 1
	s_waitcnt lgkmcnt(0)
	v_mfma_f32_16x16x32_bf16 v[126:129], v[152:155], v[184:187], v[126:129]
	v_mfma_f32_16x16x32_bf16 v[122:125], v[160:163], v[184:187], v[122:125]
	v_mfma_f32_16x16x32_bf16 v[110:113], v[152:155], v[192:195], v[110:113]
	v_mfma_f32_16x16x32_bf16 v[106:109], v[160:163], v[192:195], v[106:109]
	v_mfma_f32_16x16x32_bf16 v[94:97], v[152:155], v[200:203], v[94:97]
	v_mfma_f32_16x16x32_bf16 v[90:93], v[160:163], v[200:203], v[90:93]
	v_mfma_f32_16x16x32_bf16 v[78:81], v[152:155], v[208:211], v[78:81]
	v_mfma_f32_16x16x32_bf16 v[74:77], v[160:163], v[208:211], v[74:77]
	v_mfma_f32_16x16x32_bf16 v[126:129], v[156:159], v[188:191], v[126:129]
	v_mfma_f32_16x16x32_bf16 v[122:125], v[164:167], v[188:191], v[122:125]
	v_mfma_f32_16x16x32_bf16 v[110:113], v[156:159], v[196:199], v[110:113]
	v_mfma_f32_16x16x32_bf16 v[106:109], v[164:167], v[196:199], v[106:109]
	v_mfma_f32_16x16x32_bf16 v[94:97], v[156:159], v[204:207], v[94:97]
	v_mfma_f32_16x16x32_bf16 v[90:93], v[164:167], v[204:207], v[90:93]
	v_mfma_f32_16x16x32_bf16 v[78:81], v[156:159], v[212:215], v[78:81]
	v_mfma_f32_16x16x32_bf16 v[74:77], v[164:167], v[212:215], v[74:77]
	s_setprio 0
	s_setprio 1
	v_mfma_f32_16x16x32_bf16 v[118:121], v[168:171], v[184:187], v[118:121]
	v_mfma_f32_16x16x32_bf16 v[114:117], v[176:179], v[184:187], v[114:117]
	v_mfma_f32_16x16x32_bf16 v[102:105], v[168:171], v[192:195], v[102:105]
	v_mfma_f32_16x16x32_bf16 v[98:101], v[176:179], v[192:195], v[98:101]
	v_mfma_f32_16x16x32_bf16 v[86:89], v[168:171], v[200:203], v[86:89]
	v_mfma_f32_16x16x32_bf16 v[82:85], v[176:179], v[200:203], v[82:85]
	v_mfma_f32_16x16x32_bf16 v[70:73], v[168:171], v[208:211], v[70:73]
	v_mfma_f32_16x16x32_bf16 v[66:69], v[176:179], v[208:211], v[66:69]
	v_mfma_f32_16x16x32_bf16 v[118:121], v[172:175], v[188:191], v[118:121]
	v_mfma_f32_16x16x32_bf16 v[114:117], v[180:183], v[188:191], v[114:117]
	v_mfma_f32_16x16x32_bf16 v[102:105], v[172:175], v[196:199], v[102:105]
	v_mfma_f32_16x16x32_bf16 v[98:101], v[180:183], v[196:199], v[98:101]
	v_mfma_f32_16x16x32_bf16 v[86:89], v[172:175], v[204:207], v[86:89]
	v_mfma_f32_16x16x32_bf16 v[82:85], v[180:183], v[204:207], v[82:85]
	v_mfma_f32_16x16x32_bf16 v[70:73], v[172:175], v[212:215], v[70:73]
	v_mfma_f32_16x16x32_bf16 v[66:69], v[180:183], v[212:215], v[66:69]
	s_setprio 0
	s_barrier
	s_add_i32 s24, s49, s30
	v_lshl_add_u64 v[216:217], v[216:217], 0, s[6:7]
	s_mov_b32 m0, s24
	ds_read_b128 v[184:187], v151 offset:49152
	ds_read_b128 v[188:191], v151 offset:50176
	ds_read_b128 v[192:195], v151 offset:51200
	ds_read_b128 v[196:199], v151 offset:52224
	ds_read_b128 v[200:203], v151 offset:53248
	ds_read_b128 v[204:207], v151 offset:54272
	ds_read_b128 v[208:211], v151 offset:55296
	ds_read_b128 v[212:215], v151 offset:56320
	global_load_lds_dwordx4 v[216:217], off nt
	s_add_i32 m0, s24, 0x2000
	s_add_u32 s22, s22, 0x80080
	v_lshl_add_u64 v[216:217], v[218:219], 0, s[6:7]
	s_addc_u32 s23, s23, 0
	s_add_i32 s24, s50, s30
	global_load_lds_dwordx4 v[216:217], off nt
	v_lshl_add_u64 v[216:217], s[22:23], 0, v[132:133]
	s_mov_b32 m0, s24
	s_nop 0
	global_load_lds_dwordx4 v[216:217], off nt
	v_lshl_add_u64 v[216:217], s[22:23], 0, v[136:137]
	s_add_i32 m0, s24, 0x2000
	s_nop 0
	global_load_lds_dwordx4 v[216:217], off nt
	v_lshl_add_u64 v[216:217], v[220:221], 0, s[6:7]
	s_mov_b32 m0, s38
	s_nop 0
	global_load_lds_dwordx4 v[216:217], off
	v_lshl_add_u64 v[216:217], v[222:223], 0, s[6:7]
	s_mov_b32 m0, s39
	s_nop 0
	global_load_lds_dwordx4 v[216:217], off
	s_waitcnt vmcnt(8)
	s_waitcnt lgkmcnt(0)
	s_barrier
	s_setprio 1
	s_waitcnt lgkmcnt(0)
	v_mfma_f32_16x16x32_bf16 v[62:65], v[152:155], v[184:187], v[62:65]
	v_mfma_f32_16x16x32_bf16 v[58:61], v[160:163], v[184:187], v[58:61]
	v_mfma_f32_16x16x32_bf16 v[46:49], v[152:155], v[192:195], v[46:49]
	v_mfma_f32_16x16x32_bf16 v[42:45], v[160:163], v[192:195], v[42:45]
	v_mfma_f32_16x16x32_bf16 v[30:33], v[152:155], v[200:203], v[30:33]
	v_mfma_f32_16x16x32_bf16 v[26:29], v[160:163], v[200:203], v[26:29]
	v_mfma_f32_16x16x32_bf16 v[14:17], v[152:155], v[208:211], v[14:17]
	v_mfma_f32_16x16x32_bf16 v[10:13], v[160:163], v[208:211], v[10:13]
	v_mfma_f32_16x16x32_bf16 v[62:65], v[156:159], v[188:191], v[62:65]
	v_mfma_f32_16x16x32_bf16 v[58:61], v[164:167], v[188:191], v[58:61]
	v_mfma_f32_16x16x32_bf16 v[46:49], v[156:159], v[196:199], v[46:49]
	v_mfma_f32_16x16x32_bf16 v[42:45], v[164:167], v[196:199], v[42:45]
	v_mfma_f32_16x16x32_bf16 v[30:33], v[156:159], v[204:207], v[30:33]
	v_mfma_f32_16x16x32_bf16 v[26:29], v[164:167], v[204:207], v[26:29]
	v_mfma_f32_16x16x32_bf16 v[14:17], v[156:159], v[212:215], v[14:17]
	v_mfma_f32_16x16x32_bf16 v[10:13], v[164:167], v[212:215], v[10:13]
	s_setprio 0
	s_setprio 1
	v_mfma_f32_16x16x32_bf16 v[54:57], v[168:171], v[184:187], v[54:57]
	v_mfma_f32_16x16x32_bf16 v[50:53], v[176:179], v[184:187], v[50:53]
	v_mfma_f32_16x16x32_bf16 v[38:41], v[168:171], v[192:195], v[38:41]
	v_mfma_f32_16x16x32_bf16 v[34:37], v[176:179], v[192:195], v[34:37]
	v_mfma_f32_16x16x32_bf16 v[22:25], v[168:171], v[200:203], v[22:25]
	v_mfma_f32_16x16x32_bf16 v[18:21], v[176:179], v[200:203], v[18:21]
	v_mfma_f32_16x16x32_bf16 v[6:9], v[168:171], v[208:211], v[6:9]
	v_mfma_f32_16x16x32_bf16 v[2:5], v[176:179], v[208:211], v[2:5]
	v_mfma_f32_16x16x32_bf16 v[54:57], v[172:175], v[188:191], v[54:57]
	v_mfma_f32_16x16x32_bf16 v[50:53], v[180:183], v[188:191], v[50:53]
	v_mfma_f32_16x16x32_bf16 v[38:41], v[172:175], v[196:199], v[38:41]
	v_mfma_f32_16x16x32_bf16 v[34:37], v[180:183], v[196:199], v[34:37]
	v_mfma_f32_16x16x32_bf16 v[22:25], v[172:175], v[204:207], v[22:25]
	v_mfma_f32_16x16x32_bf16 v[18:21], v[180:183], v[204:207], v[18:21]
	v_mfma_f32_16x16x32_bf16 v[6:9], v[172:175], v[212:215], v[6:9]
	v_mfma_f32_16x16x32_bf16 v[2:5], v[180:183], v[212:215], v[2:5]
	s_setprio 0
	s_barrier
	s_add_i32 s48, s48, 2
	s_add_u32 s20, s20, 0x100
	s_addc_u32 s21, s21, 0
	s_add_u32 s46, s46, 0x100
	s_addc_u32 s47, s47, 0
	s_cmp_gt_u32 s48, 29
	s_cbranch_scc0 .LBB0_1135
	v_readlane_b32 s44, v254, 52
	s_and_b64 vcc, exec, s[8:9]
	v_readlane_b32 s45, v254, 53
	v_readlane_b32 s46, v254, 54
	v_readlane_b32 s47, v254, 55
	s_cbranch_vccz .LBB0_1138
	s_barrier
